# v72 + nt (non-temporal) on the P0 read-once loads (x f32, W_in/W_out f32 transposes)
# speedup vs baseline: 1.0411x; 1.0358x over previous
.LBB0_5:
	s_or_b64 exec, exec, s[0:1]
	v_readlane_b32 s2, v254, 0
	v_readlane_b32 s3, v254, 1
	s_mov_b64 s[0:1], s[2:3]
	s_load_dwordx4 s[40:43], s[0:1], 0x0
	s_load_dwordx4 s[44:47], s[0:1], 0x38
	s_load_dwordx2 s[38:39], s[0:1], 0x80
	s_load_dwordx2 s[48:49], s[0:1], 0x60
	v_mbcnt_lo_u32_b32 v6, -1, 0
	v_mbcnt_hi_u32_b32 v6, -1, v6
	v_readlane_b32 s0, v254, 3
	s_load_dword s56, s[2:3], 0x88
	s_nop 0
	v_add_u32_e32 v128, s0, v6
	s_add_u32 s0, s2, 0x88
	s_addc_u32 s1, s3, 0
	v_writelane_b32 v254, s0, 9
	v_readfirstlane_b32 s10, v128
	s_cmp_lg_u32 s88, 0
	v_writelane_b32 v254, s1, 10
	v_ashrrev_i32_e32 v129, 31, v128
	s_cbranch_scc1 .LBB0_7
	v_lshlrev_b64 v[0:1], 2, v[128:129]
	s_waitcnt lgkmcnt(0)
	v_lshl_add_u64 v[2:3], s[46:47], 0, v[0:1]
	global_load_dword v4, v[2:3], off nt
	global_load_dword v5, v[2:3], off offset:2048
	s_mov_b32 s0, 0x3fb8aa3b
	s_mov_b32 s1, 0x42b17218
	v_lshl_add_u64 v[0:1], s[38:39], 0, v[0:1]
	s_waitcnt vmcnt(0)
	v_sub_f32_e32 v2, v5, v4
	v_mul_f32_e32 v3, 0x3fb8aa3b, v2
	v_fma_f32 v4, v2, s0, -v3
	v_rndne_f32_e32 v5, v3
	v_fmamk_f32 v4, v2, 0x32a5705f, v4
	v_sub_f32_e32 v3, v3, v5
	v_add_f32_e32 v3, v3, v4
	v_cvt_i32_f32_e32 v5, v5
	v_exp_f32_e32 v3, v3
	s_mov_b32 s0, 0xc2ce8ed0
	v_cmp_ngt_f32_e32 vcc, s0, v2
	v_mov_b32_e32 v4, 0x7f800000
	v_ldexp_f32 v3, v3, v5
	v_cndmask_b32_e32 v3, 0, v3, vcc
	v_cmp_nlt_f32_e32 vcc, s1, v2
	s_nop 1
	v_cndmask_b32_e32 v2, v4, v3, vcc
	v_add_f32_e32 v2, 1.0, v2
	v_div_scale_f32 v3, s[0:1], v2, v2, 1.0
	v_rcp_f32_e32 v4, v3
	v_div_scale_f32 v5, vcc, 1.0, v2, 1.0
	v_fma_f32 v7, -v3, v4, 1.0
	v_fmac_f32_e32 v4, v7, v4
	v_mul_f32_e32 v7, v5, v4
	v_fma_f32 v8, -v3, v7, v5
	v_fmac_f32_e32 v7, v8, v4
	v_fma_f32 v3, -v3, v7, v5
	v_div_fmas_f32 v3, v3, v4, v7
	v_add_co_u32_e32 v0, vcc, 0xf80000, v0
	v_div_fixup_f32 v2, v3, v2, 1.0
	s_nop 0
	v_addc_co_u32_e32 v1, vcc, 0, v1, vcc
	global_store_dword v[0:1], v2, off

.LBB0_69:
	v_and_b32_e32 v162, 63, v6
	v_cndmask_b32_e64 v0, 0, 1, s[6:7]
	v_cmp_ne_u32_e64 s[34:35], 1, v0
	s_andn2_b64 vcc, exec, s[6:7]
	v_and_b32_e32 v166, 31, v6
	v_lshrrev_b32_e32 v167, 5, v162
	s_cbranch_vccnz .LBB0_71
	v_sub_u32_e64 v0, s53, 1 clamp
	v_cmp_gt_u32_e32 vcc, s53, v166
	s_ashr_i32 s9, s8, 31
	v_mov_b32_e32 v3, 0
	v_cndmask_b32_e32 v2, v0, v166, vcc
	v_add_u32_e32 v0, s52, v167
	v_mad_i64_i32 v[0:1], s[6:7], v0, s14, 0
	v_lshl_add_u64 v[0:1], v[0:1], 2, s[10:11]
	v_lshl_add_u64 v[0:1], s[8:9], 2, v[0:1]
	v_lshlrev_b32_e32 v2, 2, v2
	s_mov_b32 s7, 0
	v_lshl_add_u64 v[0:1], v[0:1], 0, v[2:3]
	s_lshl_b32 s6, s14, 3
	v_lshl_add_u64 v[2:3], v[0:1], 0, s[6:7]
	s_lshl_b32 s6, s14, 4
	v_lshl_add_u64 v[4:5], v[0:1], 0, s[6:7]
	s_mul_i32 s6, s14, 24
	v_lshl_add_u64 v[6:7], v[0:1], 0, s[6:7]
	s_lshl_b32 s6, s14, 5
	v_lshl_add_u64 v[8:9], v[0:1], 0, s[6:7]
	s_mul_i32 s6, s14, 40
	v_lshl_add_u64 v[10:11], v[0:1], 0, s[6:7]
	s_mul_i32 s6, s14, 48
	v_lshl_add_u64 v[12:13], v[0:1], 0, s[6:7]
	s_mul_i32 s6, s14, 56
	v_lshl_add_u64 v[14:15], v[0:1], 0, s[6:7]
	s_lshl_b32 s6, s14, 6
	global_load_dword v165, v[0:1], off nt
	global_load_dword v163, v[2:3], off nt
	global_load_dword v164, v[4:5], off nt
	global_load_dword v168, v[6:7], off nt
	global_load_dword v169, v[8:9], off nt
	global_load_dword v171, v[10:11], off nt
	global_load_dword v170, v[12:13], off nt
	global_load_dword v172, v[14:15], off nt
	v_lshl_add_u64 v[2:3], v[0:1], 0, s[6:7]
	s_mul_i32 s6, s14, 0x48
	v_lshl_add_u64 v[4:5], v[0:1], 0, s[6:7]
	s_mul_i32 s6, s14, 0x50
	v_lshl_add_u64 v[6:7], v[0:1], 0, s[6:7]
	s_mul_i32 s6, s14, 0x58
	v_lshl_add_u64 v[8:9], v[0:1], 0, s[6:7]
	s_mul_i32 s6, s14, 0x60
	v_lshl_add_u64 v[10:11], v[0:1], 0, s[6:7]
	s_mul_i32 s6, s14, 0x68
	v_lshl_add_u64 v[12:13], v[0:1], 0, s[6:7]
	s_mul_i32 s6, s14, 0x70
	v_lshl_add_u64 v[14:15], v[0:1], 0, s[6:7]
	s_mul_i32 s6, s14, 0x78
	v_lshl_add_u64 v[16:17], v[0:1], 0, s[6:7]
	s_lshl_b32 s6, s14, 7
	global_load_dword v173, v[2:3], off nt
	global_load_dword v175, v[4:5], off nt
	global_load_dword v174, v[6:7], off nt
	global_load_dword v176, v[8:9], off nt
	global_load_dword v177, v[10:11], off nt
	global_load_dword v179, v[12:13], off nt
	global_load_dword v178, v[14:15], off nt
	global_load_dword v180, v[16:17], off nt
	v_lshl_add_u64 v[2:3], v[0:1], 0, s[6:7]
	s_mul_i32 s6, s14, 0x88
	v_lshl_add_u64 v[4:5], v[0:1], 0, s[6:7]
	s_mul_i32 s6, s14, 0x90
	v_lshl_add_u64 v[6:7], v[0:1], 0, s[6:7]
	s_mul_i32 s6, s14, 0x98
	v_lshl_add_u64 v[8:9], v[0:1], 0, s[6:7]
	s_mul_i32 s6, s14, 0xa0
	v_lshl_add_u64 v[10:11], v[0:1], 0, s[6:7]
	s_mul_i32 s6, s14, 0xa8
	v_lshl_add_u64 v[12:13], v[0:1], 0, s[6:7]
	s_mul_i32 s6, s14, 0xb0
	v_lshl_add_u64 v[14:15], v[0:1], 0, s[6:7]
	s_mul_i32 s6, s14, 0xb8
	v_lshl_add_u64 v[16:17], v[0:1], 0, s[6:7]
	s_mul_i32 s6, s14, 0xc0
	global_load_dword v189, v[2:3], off nt
	global_load_dword v191, v[4:5], off nt
	global_load_dword v190, v[6:7], off nt
	global_load_dword v192, v[8:9], off nt
	global_load_dword v193, v[10:11], off nt
	global_load_dword v195, v[12:13], off nt
	global_load_dword v194, v[14:15], off nt
	global_load_dword v196, v[16:17], off nt
	v_lshl_add_u64 v[2:3], v[0:1], 0, s[6:7]
	s_mul_i32 s6, s14, 0xc8
	v_lshl_add_u64 v[4:5], v[0:1], 0, s[6:7]
	s_mul_i32 s6, s14, 0xd0
	v_lshl_add_u64 v[6:7], v[0:1], 0, s[6:7]
	s_mul_i32 s6, s14, 0xd8
	v_lshl_add_u64 v[8:9], v[0:1], 0, s[6:7]
	s_mul_i32 s6, s14, 0xe0
	v_lshl_add_u64 v[10:11], v[0:1], 0, s[6:7]
	s_mul_i32 s6, s14, 0xe8
	v_lshl_add_u64 v[12:13], v[0:1], 0, s[6:7]
	s_mul_i32 s6, s14, 0xf0
	v_lshl_add_u64 v[14:15], v[0:1], 0, s[6:7]
	s_mul_i32 s6, s14, 0xf8
	v_lshl_add_u64 v[0:1], v[0:1], 0, s[6:7]
	global_load_dword v206, v[2:3], off nt
	global_load_dword v208, v[4:5], off nt
	global_load_dword v207, v[6:7], off nt
	global_load_dword v209, v[8:9], off nt
	global_load_dword v210, v[10:11], off nt
	global_load_dword v212, v[12:13], off nt
	global_load_dword v211, v[14:15], off nt
	global_load_dword v213, v[0:1], off nt
.LBB0_71:
	v_cndmask_b32_e64 v0, 0, 1, s[0:1]
	v_cmp_ne_u32_e64 s[36:37], 1, v0
	s_andn2_b64 vcc, exec, s[0:1]
	s_cbranch_vccnz .LBB0_73
	v_sub_u32_e64 v0, s65, 1 clamp
	v_cmp_gt_u32_e32 vcc, s65, v166
	s_ashr_i32 s3, s2, 31
	v_mov_b32_e32 v3, 0
	v_cndmask_b32_e32 v2, v0, v166, vcc
	v_add_u32_e32 v0, s50, v167
	v_mad_i64_i32 v[0:1], s[0:1], v0, s12, 0
	v_lshl_add_u64 v[0:1], v[0:1], 2, s[4:5]
	v_lshl_add_u64 v[0:1], s[2:3], 2, v[0:1]
	v_lshlrev_b32_e32 v2, 2, v2
	s_mov_b32 s1, 0
	v_lshl_add_u64 v[0:1], v[0:1], 0, v[2:3]
	s_lshl_b32 s0, s12, 3
	v_lshl_add_u64 v[2:3], v[0:1], 0, s[0:1]
	s_lshl_b32 s0, s12, 4
	v_lshl_add_u64 v[4:5], v[0:1], 0, s[0:1]
	s_mul_i32 s0, s12, 24
	v_lshl_add_u64 v[6:7], v[0:1], 0, s[0:1]
	s_lshl_b32 s0, s12, 5
	v_lshl_add_u64 v[8:9], v[0:1], 0, s[0:1]
	s_mul_i32 s0, s12, 40
	v_lshl_add_u64 v[10:11], v[0:1], 0, s[0:1]
	s_mul_i32 s0, s12, 48
	v_lshl_add_u64 v[12:13], v[0:1], 0, s[0:1]
	s_mul_i32 s0, s12, 56
	v_lshl_add_u64 v[14:15], v[0:1], 0, s[0:1]
	s_lshl_b32 s0, s12, 6
	global_load_dword v197, v[0:1], off nt
	global_load_dword v188, v[2:3], off nt
	global_load_dword v187, v[4:5], off nt
	global_load_dword v186, v[6:7], off nt
	global_load_dword v185, v[8:9], off nt
	global_load_dword v184, v[10:11], off nt
	global_load_dword v183, v[12:13], off nt
	global_load_dword v182, v[14:15], off nt
	v_lshl_add_u64 v[2:3], v[0:1], 0, s[0:1]
	s_mul_i32 s0, s12, 0x48
	v_lshl_add_u64 v[4:5], v[0:1], 0, s[0:1]
	s_mul_i32 s0, s12, 0x50
	v_lshl_add_u64 v[6:7], v[0:1], 0, s[0:1]
	s_mul_i32 s0, s12, 0x58
	v_lshl_add_u64 v[8:9], v[0:1], 0, s[0:1]
	s_mul_i32 s0, s12, 0x60
	v_lshl_add_u64 v[10:11], v[0:1], 0, s[0:1]
	s_mul_i32 s0, s12, 0x68
	v_lshl_add_u64 v[12:13], v[0:1], 0, s[0:1]
	s_mul_i32 s0, s12, 0x70
	v_lshl_add_u64 v[14:15], v[0:1], 0, s[0:1]
	s_mul_i32 s0, s12, 0x78
	v_lshl_add_u64 v[16:17], v[0:1], 0, s[0:1]
	s_lshl_b32 s0, s12, 7
	global_load_dword v205, v[2:3], off nt
	global_load_dword v204, v[4:5], off nt
	global_load_dword v203, v[6:7], off nt
	global_load_dword v202, v[8:9], off nt
	global_load_dword v201, v[10:11], off nt
	global_load_dword v200, v[12:13], off nt
	global_load_dword v199, v[14:15], off nt
	global_load_dword v198, v[16:17], off nt
	v_lshl_add_u64 v[2:3], v[0:1], 0, s[0:1]
	s_mul_i32 s0, s12, 0x88
	v_lshl_add_u64 v[4:5], v[0:1], 0, s[0:1]
	s_mul_i32 s0, s12, 0x90
	v_lshl_add_u64 v[6:7], v[0:1], 0, s[0:1]
	s_mul_i32 s0, s12, 0x98
	v_lshl_add_u64 v[8:9], v[0:1], 0, s[0:1]
	s_mul_i32 s0, s12, 0xa0
	v_lshl_add_u64 v[10:11], v[0:1], 0, s[0:1]
	s_mul_i32 s0, s12, 0xa8
	v_lshl_add_u64 v[12:13], v[0:1], 0, s[0:1]
	s_mul_i32 s0, s12, 0xb0
	v_lshl_add_u64 v[14:15], v[0:1], 0, s[0:1]
	s_mul_i32 s0, s12, 0xb8
	v_lshl_add_u64 v[16:17], v[0:1], 0, s[0:1]
	s_mul_i32 s0, s12, 0xc0
	global_load_dword v221, v[2:3], off nt
	global_load_dword v220, v[4:5], off nt
	global_load_dword v219, v[6:7], off nt
	global_load_dword v218, v[8:9], off nt
	global_load_dword v217, v[10:11], off nt
	global_load_dword v216, v[12:13], off nt
	global_load_dword v215, v[14:15], off nt
	global_load_dword v214, v[16:17], off nt
	v_lshl_add_u64 v[2:3], v[0:1], 0, s[0:1]
	s_mul_i32 s0, s12, 0xc8
	v_lshl_add_u64 v[4:5], v[0:1], 0, s[0:1]
	s_mul_i32 s0, s12, 0xd0
	v_lshl_add_u64 v[6:7], v[0:1], 0, s[0:1]
	s_mul_i32 s0, s12, 0xd8
	v_lshl_add_u64 v[8:9], v[0:1], 0, s[0:1]
	s_mul_i32 s0, s12, 0xe0
	v_lshl_add_u64 v[10:11], v[0:1], 0, s[0:1]
	s_mul_i32 s0, s12, 0xe8
	v_lshl_add_u64 v[12:13], v[0:1], 0, s[0:1]
	s_mul_i32 s0, s12, 0xf0
	v_lshl_add_u64 v[14:15], v[0:1], 0, s[0:1]
	s_mul_i32 s0, s12, 0xf8
	v_lshl_add_u64 v[0:1], v[0:1], 0, s[0:1]
	global_load_dword v223, v[2:3], off nt
	global_load_dword v222, v[4:5], off nt
	global_load_dword v224, v[6:7], off nt
	global_load_dword v225, v[8:9], off nt
	global_load_dword v226, v[10:11], off nt
	global_load_dword v228, v[12:13], off nt
	global_load_dword v227, v[14:15], off nt
	global_load_dword v229, v[0:1], off nt
.LBB0_73:
	s_ashr_i32 s89, s88, 31
	s_lshl_b64 s[46:47], s[88:89], 9
	v_lshl_add_u64 v[130:131], s[46:47], 0, v[128:129]
	s_mov_b64 s[2:3], 0x208000
	v_cmp_gt_u64_e64 s[0:1], s[2:3], v[130:131]
	s_and_saveexec_b64 s[4:5], s[0:1]
	s_cbranch_execz .LBB0_75
	v_lshlrev_b64 v[0:1], 5, v[130:131]
	s_brev_b32 s8, 63
	s_mov_b64 s[6:7], 0x200000
	v_lshl_add_u64 v[2:3], s[40:41], 0, v[0:1]
	v_lshl_add_u64 v[0:1], s[42:43], 0, v[0:1]
	s_mov_b32 s9, -1
	v_lshl_add_u64 v[0:1], v[0:1], 0, s[8:9]
	v_cmp_gt_u64_e32 vcc, s[6:7], v[130:131]
	s_nop 1
	v_cndmask_b32_e32 v1, v1, v3, vcc
	v_cndmask_b32_e32 v0, v0, v2, vcc
	global_load_dwordx4 v[124:127], v[0:1], off nt
	global_load_dwordx4 v[120:123], v[0:1], off offset:16 nt
.LBB0_75:
	s_or_b64 exec, exec, s[4:5]
	s_ashr_i32 s57, s56, 31
	s_lshl_b64 s[30:31], s[56:57], 9
	v_lshl_add_u64 v[132:133], s[30:31], 0, v[130:131]
	v_cmp_gt_u64_e64 s[2:3], s[2:3], v[132:133]
	s_and_saveexec_b64 s[4:5], s[2:3]
	s_cbranch_execz .LBB0_77
	v_lshlrev_b64 v[0:1], 5, v[132:133]
	s_brev_b32 s8, 63
	s_mov_b64 s[6:7], 0x200000
	v_lshl_add_u64 v[2:3], s[40:41], 0, v[0:1]
	v_lshl_add_u64 v[0:1], s[42:43], 0, v[0:1]
	s_mov_b32 s9, -1
	v_lshl_add_u64 v[0:1], v[0:1], 0, s[8:9]
	v_cmp_gt_u64_e32 vcc, s[6:7], v[132:133]
	s_nop 1
	v_cndmask_b32_e32 v5, v1, v3, vcc
	v_cndmask_b32_e32 v4, v0, v2, vcc
	global_load_dwordx4 v[0:3], v[4:5], off offset:16 nt
	s_nop 0
	global_load_dwordx4 v[4:7], v[4:5], off nt
.LBB0_77:
	s_or_b64 exec, exec, s[4:5]
	v_lshl_add_u64 v[134:135], v[132:133], 0, s[30:31]
	s_mov_b64 s[6:7], 0x208000
	v_cmp_gt_u64_e64 s[4:5], s[6:7], v[134:135]
	s_and_saveexec_b64 s[8:9], s[4:5]
	s_cbranch_execz .LBB0_79
	v_lshlrev_b64 v[8:9], 5, v[134:135]
	s_brev_b32 s12, 63
	s_mov_b64 s[10:11], 0x200000
	v_lshl_add_u64 v[10:11], s[40:41], 0, v[8:9]
	v_lshl_add_u64 v[8:9], s[42:43], 0, v[8:9]
	s_mov_b32 s13, -1
	v_lshl_add_u64 v[8:9], v[8:9], 0, s[12:13]
	v_cmp_gt_u64_e32 vcc, s[10:11], v[134:135]
	s_nop 1
	v_cndmask_b32_e32 v13, v9, v11, vcc
	v_cndmask_b32_e32 v12, v8, v10, vcc
	global_load_dwordx4 v[8:11], v[12:13], off offset:16 nt
	s_nop 0
	global_load_dwordx4 v[12:15], v[12:13], off nt
.LBB0_79:
	s_or_b64 exec, exec, s[8:9]
	v_lshl_add_u64 v[136:137], v[134:135], 0, s[30:31]
	v_cmp_gt_u64_e64 s[6:7], s[6:7], v[136:137]
	s_and_saveexec_b64 s[8:9], s[6:7]
	s_cbranch_execz .LBB0_81
	v_lshlrev_b64 v[16:17], 5, v[136:137]
	s_brev_b32 s12, 63
	s_mov_b64 s[10:11], 0x200000
	v_lshl_add_u64 v[18:19], s[40:41], 0, v[16:17]
	v_lshl_add_u64 v[16:17], s[42:43], 0, v[16:17]
	s_mov_b32 s13, -1
	v_lshl_add_u64 v[16:17], v[16:17], 0, s[12:13]
	v_cmp_gt_u64_e32 vcc, s[10:11], v[136:137]
	s_nop 1
	v_cndmask_b32_e32 v21, v17, v19, vcc
	v_cndmask_b32_e32 v20, v16, v18, vcc
	global_load_dwordx4 v[16:19], v[20:21], off offset:16 nt
	s_nop 0
	global_load_dwordx4 v[20:23], v[20:21], off nt
.LBB0_81:
	s_or_b64 exec, exec, s[8:9]
	v_lshl_add_u64 v[138:139], v[136:137], 0, s[30:31]
	s_mov_b64 s[10:11], 0x208000
	v_cmp_gt_u64_e64 s[8:9], s[10:11], v[138:139]
	s_and_saveexec_b64 s[12:13], s[8:9]
	s_cbranch_execz .LBB0_83
	v_lshlrev_b64 v[24:25], 5, v[138:139]
	s_brev_b32 s16, 63
	s_mov_b64 s[14:15], 0x200000
	v_lshl_add_u64 v[26:27], s[40:41], 0, v[24:25]
	v_lshl_add_u64 v[24:25], s[42:43], 0, v[24:25]
	s_mov_b32 s17, -1
	v_lshl_add_u64 v[24:25], v[24:25], 0, s[16:17]
	v_cmp_gt_u64_e32 vcc, s[14:15], v[138:139]
	s_nop 1
	v_cndmask_b32_e32 v29, v25, v27, vcc
	v_cndmask_b32_e32 v28, v24, v26, vcc
	global_load_dwordx4 v[24:27], v[28:29], off offset:16 nt
	s_nop 0
	global_load_dwordx4 v[28:31], v[28:29], off nt
.LBB0_83:
	s_or_b64 exec, exec, s[12:13]
	v_lshl_add_u64 v[140:141], v[138:139], 0, s[30:31]
	v_cmp_gt_u64_e64 s[10:11], s[10:11], v[140:141]
	s_and_saveexec_b64 s[12:13], s[10:11]
	s_cbranch_execz .LBB0_85
	v_lshlrev_b64 v[32:33], 5, v[140:141]
	s_brev_b32 s16, 63
	s_mov_b64 s[14:15], 0x200000
	v_lshl_add_u64 v[34:35], s[40:41], 0, v[32:33]
	v_lshl_add_u64 v[32:33], s[42:43], 0, v[32:33]
	s_mov_b32 s17, -1
	v_lshl_add_u64 v[32:33], v[32:33], 0, s[16:17]
	v_cmp_gt_u64_e32 vcc, s[14:15], v[140:141]
	s_nop 1
	v_cndmask_b32_e32 v37, v33, v35, vcc
	v_cndmask_b32_e32 v36, v32, v34, vcc
	global_load_dwordx4 v[32:35], v[36:37], off offset:16 nt
	s_nop 0
	global_load_dwordx4 v[36:39], v[36:37], off nt
.LBB0_85:
	s_or_b64 exec, exec, s[12:13]
	v_lshl_add_u64 v[142:143], v[140:141], 0, s[30:31]
	s_mov_b64 s[14:15], 0x208000
	v_cmp_gt_u64_e64 s[12:13], s[14:15], v[142:143]
	s_and_saveexec_b64 s[16:17], s[12:13]
	s_cbranch_execz .LBB0_87
	v_lshlrev_b64 v[40:41], 5, v[142:143]
	s_brev_b32 s20, 63
	s_mov_b64 s[18:19], 0x200000
	v_lshl_add_u64 v[42:43], s[40:41], 0, v[40:41]
	v_lshl_add_u64 v[40:41], s[42:43], 0, v[40:41]
	s_mov_b32 s21, -1
	v_lshl_add_u64 v[40:41], v[40:41], 0, s[20:21]
	v_cmp_gt_u64_e32 vcc, s[18:19], v[142:143]
	s_nop 1
	v_cndmask_b32_e32 v45, v41, v43, vcc
	v_cndmask_b32_e32 v44, v40, v42, vcc
	global_load_dwordx4 v[40:43], v[44:45], off offset:16 nt
	s_nop 0
	global_load_dwordx4 v[44:47], v[44:45], off nt
.LBB0_87:
	s_or_b64 exec, exec, s[16:17]
	v_lshl_add_u64 v[144:145], v[142:143], 0, s[30:31]
	v_cmp_gt_u64_e64 s[14:15], s[14:15], v[144:145]
	s_and_saveexec_b64 s[16:17], s[14:15]
	s_cbranch_execz .LBB0_89
	v_lshlrev_b64 v[48:49], 5, v[144:145]
	s_brev_b32 s20, 63
	s_mov_b64 s[18:19], 0x200000
	v_lshl_add_u64 v[50:51], s[40:41], 0, v[48:49]
	v_lshl_add_u64 v[48:49], s[42:43], 0, v[48:49]
	s_mov_b32 s21, -1
	v_lshl_add_u64 v[48:49], v[48:49], 0, s[20:21]
	v_cmp_gt_u64_e32 vcc, s[18:19], v[144:145]
	s_nop 1
	v_cndmask_b32_e32 v53, v49, v51, vcc
	v_cndmask_b32_e32 v52, v48, v50, vcc
	global_load_dwordx4 v[48:51], v[52:53], off offset:16 nt
	s_nop 0
	global_load_dwordx4 v[52:55], v[52:53], off nt
.LBB0_89:
	s_or_b64 exec, exec, s[16:17]
	v_lshl_add_u64 v[146:147], v[144:145], 0, s[30:31]
	s_mov_b64 s[18:19], 0x208000
	v_cmp_gt_u64_e64 s[16:17], s[18:19], v[146:147]
	s_and_saveexec_b64 s[20:21], s[16:17]
	s_cbranch_execz .LBB0_91
	v_lshlrev_b64 v[56:57], 5, v[146:147]
	s_brev_b32 s24, 63
	s_mov_b64 s[22:23], 0x200000
	v_lshl_add_u64 v[58:59], s[40:41], 0, v[56:57]
	v_lshl_add_u64 v[56:57], s[42:43], 0, v[56:57]
	s_mov_b32 s25, -1
	v_lshl_add_u64 v[56:57], v[56:57], 0, s[24:25]
	v_cmp_gt_u64_e32 vcc, s[22:23], v[146:147]
	s_nop 1
	v_cndmask_b32_e32 v61, v57, v59, vcc
	v_cndmask_b32_e32 v60, v56, v58, vcc
	global_load_dwordx4 v[56:59], v[60:61], off offset:16 nt
	s_nop 0
	global_load_dwordx4 v[60:63], v[60:61], off nt
.LBB0_91:
	s_or_b64 exec, exec, s[20:21]
	v_lshl_add_u64 v[148:149], v[146:147], 0, s[30:31]
	v_cmp_gt_u64_e64 s[18:19], s[18:19], v[148:149]
	s_and_saveexec_b64 s[20:21], s[18:19]
	s_cbranch_execz .LBB0_93
	v_lshlrev_b64 v[64:65], 5, v[148:149]
	s_brev_b32 s24, 63
	s_mov_b64 s[22:23], 0x200000
	v_lshl_add_u64 v[66:67], s[40:41], 0, v[64:65]
	v_lshl_add_u64 v[64:65], s[42:43], 0, v[64:65]
	s_mov_b32 s25, -1
	v_lshl_add_u64 v[64:65], v[64:65], 0, s[24:25]
	v_cmp_gt_u64_e32 vcc, s[22:23], v[148:149]
	s_nop 1
	v_cndmask_b32_e32 v69, v65, v67, vcc
	v_cndmask_b32_e32 v68, v64, v66, vcc
	global_load_dwordx4 v[64:67], v[68:69], off offset:16 nt
	s_nop 0
	global_load_dwordx4 v[68:71], v[68:69], off nt
.LBB0_93:
	s_or_b64 exec, exec, s[20:21]
	v_lshl_add_u64 v[150:151], v[148:149], 0, s[30:31]
	s_mov_b64 s[22:23], 0x208000
	v_cmp_gt_u64_e64 s[20:21], s[22:23], v[150:151]
	s_and_saveexec_b64 s[24:25], s[20:21]
	s_cbranch_execz .LBB0_95
	v_lshlrev_b64 v[72:73], 5, v[150:151]
	s_brev_b32 s28, 63
	s_mov_b64 s[26:27], 0x200000
	v_lshl_add_u64 v[74:75], s[40:41], 0, v[72:73]
	v_lshl_add_u64 v[72:73], s[42:43], 0, v[72:73]
	s_mov_b32 s29, -1
	v_lshl_add_u64 v[72:73], v[72:73], 0, s[28:29]
	v_cmp_gt_u64_e32 vcc, s[26:27], v[150:151]
	s_nop 1
	v_cndmask_b32_e32 v77, v73, v75, vcc
	v_cndmask_b32_e32 v76, v72, v74, vcc
	global_load_dwordx4 v[72:75], v[76:77], off offset:16 nt
	s_nop 0
	global_load_dwordx4 v[76:79], v[76:77], off nt
.LBB0_95:
	s_or_b64 exec, exec, s[24:25]
	v_lshl_add_u64 v[152:153], v[150:151], 0, s[30:31]
	v_cmp_gt_u64_e64 s[22:23], s[22:23], v[152:153]
	s_and_saveexec_b64 s[24:25], s[22:23]
	s_cbranch_execz .LBB0_97
	v_lshlrev_b64 v[80:81], 5, v[152:153]
	s_brev_b32 s28, 63
	s_mov_b64 s[26:27], 0x200000
	v_lshl_add_u64 v[82:83], s[40:41], 0, v[80:81]
	v_lshl_add_u64 v[80:81], s[42:43], 0, v[80:81]
	s_mov_b32 s29, -1
	v_lshl_add_u64 v[80:81], v[80:81], 0, s[28:29]
	v_cmp_gt_u64_e32 vcc, s[26:27], v[152:153]
	s_nop 1
	v_cndmask_b32_e32 v85, v81, v83, vcc
	v_cndmask_b32_e32 v84, v80, v82, vcc
	global_load_dwordx4 v[80:83], v[84:85], off offset:16 nt
	s_nop 0
	global_load_dwordx4 v[84:87], v[84:85], off nt
.LBB0_97:
	s_or_b64 exec, exec, s[24:25]
	v_lshl_add_u64 v[154:155], v[152:153], 0, s[30:31]
	s_mov_b64 s[26:27], 0x208000
	v_cmp_gt_u64_e64 s[24:25], s[26:27], v[154:155]
	s_and_saveexec_b64 s[28:29], s[24:25]
	s_cbranch_execz .LBB0_99
	v_lshlrev_b64 v[88:89], 5, v[154:155]
	s_brev_b32 s62, 63
	s_mov_b64 s[60:61], 0x200000
	v_lshl_add_u64 v[90:91], s[40:41], 0, v[88:89]
	v_lshl_add_u64 v[88:89], s[42:43], 0, v[88:89]
	s_mov_b32 s63, -1
	v_lshl_add_u64 v[88:89], v[88:89], 0, s[62:63]
	v_cmp_gt_u64_e32 vcc, s[60:61], v[154:155]
	s_nop 1
	v_cndmask_b32_e32 v93, v89, v91, vcc
	v_cndmask_b32_e32 v92, v88, v90, vcc
	global_load_dwordx4 v[88:91], v[92:93], off offset:16 nt
	s_nop 0
	global_load_dwordx4 v[92:95], v[92:93], off nt
.LBB0_99:
	s_or_b64 exec, exec, s[28:29]
	v_lshl_add_u64 v[156:157], v[154:155], 0, s[30:31]
	v_cmp_gt_u64_e64 s[26:27], s[26:27], v[156:157]
	s_and_saveexec_b64 s[28:29], s[26:27]
	s_cbranch_execz .LBB0_101
	v_lshlrev_b64 v[96:97], 5, v[156:157]
	s_brev_b32 s62, 63
	s_mov_b64 s[60:61], 0x200000
	v_lshl_add_u64 v[98:99], s[40:41], 0, v[96:97]
	v_lshl_add_u64 v[96:97], s[42:43], 0, v[96:97]
	s_mov_b32 s63, -1
	v_lshl_add_u64 v[96:97], v[96:97], 0, s[62:63]
	v_cmp_gt_u64_e32 vcc, s[60:61], v[156:157]
	s_nop 1
	v_cndmask_b32_e32 v101, v97, v99, vcc
	v_cndmask_b32_e32 v100, v96, v98, vcc
	global_load_dwordx4 v[96:99], v[100:101], off offset:16 nt
	s_nop 0
	global_load_dwordx4 v[100:103], v[100:101], off nt
.LBB0_101:
	s_or_b64 exec, exec, s[28:29]
	v_lshl_add_u64 v[158:159], v[156:157], 0, s[30:31]
	s_mov_b64 s[60:61], 0x208000
	v_cmp_gt_u64_e64 s[28:29], s[60:61], v[158:159]
	s_and_saveexec_b64 s[62:63], s[28:29]
	s_cbranch_execz .LBB0_103
	v_lshlrev_b64 v[104:105], 5, v[158:159]
	s_brev_b32 s70, 63
	s_mov_b64 s[68:69], 0x200000
	v_lshl_add_u64 v[106:107], s[40:41], 0, v[104:105]
	v_lshl_add_u64 v[104:105], s[42:43], 0, v[104:105]
	s_mov_b32 s71, -1
	v_lshl_add_u64 v[104:105], v[104:105], 0, s[70:71]
	v_cmp_gt_u64_e32 vcc, s[68:69], v[158:159]
	s_nop 1
	v_cndmask_b32_e32 v109, v105, v107, vcc
	v_cndmask_b32_e32 v108, v104, v106, vcc
	global_load_dwordx4 v[104:107], v[108:109], off offset:16 nt
	s_nop 0
	global_load_dwordx4 v[108:111], v[108:109], off nt
.LBB0_103:
	s_or_b64 exec, exec, s[62:63]
	v_lshl_add_u64 v[160:161], v[158:159], 0, s[30:31]
	v_cmp_gt_u64_e64 s[30:31], s[60:61], v[160:161]
	s_and_saveexec_b64 s[60:61], s[30:31]
	s_cbranch_execz .LBB0_105
	v_lshlrev_b64 v[112:113], 5, v[160:161]
	s_brev_b32 s68, 63
	s_mov_b64 s[62:63], 0x200000
	v_lshl_add_u64 v[114:115], s[40:41], 0, v[112:113]
	v_lshl_add_u64 v[112:113], s[42:43], 0, v[112:113]
	s_mov_b32 s69, -1
	v_lshl_add_u64 v[112:113], v[112:113], 0, s[68:69]
	v_cmp_gt_u64_e32 vcc, s[62:63], v[160:161]
	s_nop 1
	v_cndmask_b32_e32 v117, v113, v115, vcc
	v_cndmask_b32_e32 v116, v112, v114, vcc
	global_load_dwordx4 v[112:115], v[116:117], off offset:16 nt
	s_nop 0
	global_load_dwordx4 v[116:119], v[116:117], off nt

.LBB0_113:
	s_waitcnt vmcnt(16)
	v_add_u32_e32 v180, s36, v167
	s_add_u32 s54, s38, s54
	v_sub_u32_e64 v162, s51, 1 clamp
	v_cmp_gt_u32_e32 vcc, s51, v166
	v_mad_i64_i32 v[182:183], s[68:69], v180, s37, 0
	s_addc_u32 s55, s39, s55
	v_cndmask_b32_e32 v162, v162, v166, vcc
	v_lshl_add_u64 v[182:183], v[182:183], 2, s[52:53]
	s_ashr_i32 s51, s50, 31
	v_lshl_add_u64 v[182:183], s[50:51], 2, v[182:183]
	v_lshlrev_b32_e32 v162, 2, v162
	v_lshl_add_u64 v[182:183], v[182:183], 0, v[162:163]
	s_lshl_b32 s34, s37, 3
	v_lshl_add_u64 v[184:185], v[182:183], 0, s[34:35]
	s_lshl_b32 s34, s37, 4
	v_lshl_add_u64 v[186:187], v[182:183], 0, s[34:35]
	s_mul_i32 s34, s37, 24
	s_waitcnt vmcnt(15)
	v_lshl_add_u64 v[188:189], v[182:183], 0, s[34:35]
	s_lshl_b32 s34, s37, 5
	s_waitcnt vmcnt(13)
	v_lshl_add_u64 v[190:191], v[182:183], 0, s[34:35]
	s_mul_i32 s34, s37, 40
	s_waitcnt vmcnt(11)
	v_lshl_add_u64 v[192:193], v[182:183], 0, s[34:35]
	s_mul_i32 s34, s37, 48
	s_waitcnt vmcnt(9)
	v_lshl_add_u64 v[194:195], v[182:183], 0, s[34:35]
	s_mul_i32 s34, s37, 56
	s_waitcnt vmcnt(8)
	v_lshl_add_u64 v[196:197], v[182:183], 0, s[34:35]
	s_lshl_b32 s34, s37, 6
	global_load_dword v162, v[182:183], off nt
	global_load_dword v180, v[184:185], off nt
	global_load_dword v200, v[186:187], off nt
	global_load_dword v201, v[188:189], off nt
	global_load_dword v202, v[190:191], off nt
	global_load_dword v203, v[192:193], off nt
	global_load_dword v204, v[194:195], off nt
	global_load_dword v205, v[196:197], off nt
	v_lshl_add_u64 v[184:185], v[182:183], 0, s[34:35]
	s_mul_i32 s34, s37, 0x48
	v_lshl_add_u64 v[186:187], v[182:183], 0, s[34:35]
	s_mul_i32 s34, s37, 0x50
	v_lshl_add_u64 v[188:189], v[182:183], 0, s[34:35]
	s_mul_i32 s34, s37, 0x58
	v_lshl_add_u64 v[190:191], v[182:183], 0, s[34:35]
	s_mul_i32 s34, s37, 0x60
	v_lshl_add_u64 v[192:193], v[182:183], 0, s[34:35]
	s_mul_i32 s34, s37, 0x68
	v_lshl_add_u64 v[194:195], v[182:183], 0, s[34:35]
	s_mul_i32 s34, s37, 0x70
	v_lshl_add_u64 v[196:197], v[182:183], 0, s[34:35]
	s_mul_i32 s34, s37, 0x78
	v_lshl_add_u64 v[198:199], v[182:183], 0, s[34:35]
	s_lshl_b32 s34, s37, 7
	global_load_dword v206, v[184:185], off nt
	global_load_dword v207, v[186:187], off nt
	global_load_dword v208, v[188:189], off nt
	global_load_dword v209, v[190:191], off nt
	global_load_dword v210, v[192:193], off nt
	global_load_dword v211, v[194:195], off nt
	global_load_dword v212, v[196:197], off nt
	global_load_dword v213, v[198:199], off nt
	v_lshl_add_u64 v[184:185], v[182:183], 0, s[34:35]
	s_mul_i32 s34, s37, 0x88
	v_lshl_add_u64 v[186:187], v[182:183], 0, s[34:35]
	s_mul_i32 s34, s37, 0x90
	v_lshl_add_u64 v[188:189], v[182:183], 0, s[34:35]
	s_mul_i32 s34, s37, 0x98
	v_lshl_add_u64 v[190:191], v[182:183], 0, s[34:35]
	s_mul_i32 s34, s37, 0xa0
	v_lshl_add_u64 v[192:193], v[182:183], 0, s[34:35]
	s_mul_i32 s34, s37, 0xa8
	v_lshl_add_u64 v[194:195], v[182:183], 0, s[34:35]
	s_mul_i32 s34, s37, 0xb0
	v_lshl_add_u64 v[196:197], v[182:183], 0, s[34:35]
	s_mul_i32 s34, s37, 0xb8
	v_lshl_add_u64 v[198:199], v[182:183], 0, s[34:35]
	s_mul_i32 s34, s37, 0xc0
	global_load_dword v214, v[184:185], off nt
	global_load_dword v215, v[186:187], off nt
	global_load_dword v216, v[188:189], off nt
	global_load_dword v217, v[190:191], off nt
	global_load_dword v218, v[192:193], off nt
	global_load_dword v219, v[194:195], off nt
	s_nop 0
	global_load_dword v196, v[196:197], off nt
	s_nop 0
	global_load_dword v197, v[198:199], off nt
	v_lshl_add_u64 v[184:185], v[182:183], 0, s[34:35]
	s_mul_i32 s34, s37, 0xc8
	v_lshl_add_u64 v[186:187], v[182:183], 0, s[34:35]
	s_mul_i32 s34, s37, 0xd0
	v_lshl_add_u64 v[188:189], v[182:183], 0, s[34:35]
	s_mul_i32 s34, s37, 0xd8
	v_lshl_add_u64 v[190:191], v[182:183], 0, s[34:35]
	s_mul_i32 s34, s37, 0xe0
	v_lshl_add_u64 v[192:193], v[182:183], 0, s[34:35]
	s_mul_i32 s34, s37, 0xe8
	v_lshl_add_u64 v[194:195], v[182:183], 0, s[34:35]
	s_mul_i32 s34, s37, 0xf0
	global_load_dword v198, v[184:185], off nt
	s_nop 0
	global_load_dword v186, v[186:187], off nt
	s_nop 0
	global_load_dword v187, v[188:189], off nt
	s_nop 0
	global_load_dword v188, v[190:191], off nt
	global_load_dword v189, v[192:193], off nt
	s_nop 0
	global_load_dword v190, v[194:195], off nt
	v_lshl_add_u64 v[184:185], v[182:183], 0, s[34:35]
	s_mul_i32 s34, s37, 0xf8
	v_lshl_add_u64 v[182:183], v[182:183], 0, s[34:35]
	global_load_dword v184, v[184:185], off nt
	s_nop 0
	global_load_dword v182, v[182:183], off nt
	s_ashr_i32 s37, s36, 31
	s_lshl_b64 s[36:37], s[36:37], 1
	s_add_u32 s36, s54, s36
	s_addc_u32 s37, s55, s37
	s_add_i32 s58, s58, s59
	s_add_i32 s60, s60, s61
	s_waitcnt vmcnt(31)
	v_cndmask_b32_e32 v162, 0, v162, vcc
	s_waitcnt vmcnt(30)
	v_cndmask_b32_e32 v180, 0, v180, vcc
	ds_write2_b32 v172, v162, v180 offset1:66
	s_waitcnt vmcnt(29)
	v_cndmask_b32_e32 v162, 0, v200, vcc
	s_waitcnt vmcnt(28)
	v_cndmask_b32_e32 v180, 0, v201, vcc
	ds_write2_b32 v172, v162, v180 offset0:132 offset1:198
	s_waitcnt vmcnt(27)
	v_cndmask_b32_e32 v162, 0, v202, vcc
	s_waitcnt vmcnt(26)
	v_cndmask_b32_e32 v180, 0, v203, vcc
	ds_write2_b32 v173, v162, v180 offset0:8 offset1:74
	s_waitcnt vmcnt(25)
	v_cndmask_b32_e32 v162, 0, v204, vcc
	s_waitcnt vmcnt(24)
	v_cndmask_b32_e32 v180, 0, v205, vcc
	ds_write2_b32 v173, v162, v180 offset0:140 offset1:206
	s_waitcnt vmcnt(23)
	v_cndmask_b32_e32 v162, 0, v206, vcc
	s_waitcnt vmcnt(22)
	v_cndmask_b32_e32 v180, 0, v207, vcc
	ds_write2_b32 v174, v162, v180 offset0:16 offset1:82
	s_waitcnt vmcnt(21)
	v_cndmask_b32_e32 v162, 0, v208, vcc
	s_waitcnt vmcnt(20)
	v_cndmask_b32_e32 v180, 0, v209, vcc
	ds_write2_b32 v174, v162, v180 offset0:148 offset1:214
	s_waitcnt vmcnt(19)
	v_cndmask_b32_e32 v162, 0, v210, vcc
	s_waitcnt vmcnt(18)
	v_cndmask_b32_e32 v180, 0, v211, vcc
	ds_write2_b32 v175, v162, v180 offset0:24 offset1:90
	s_waitcnt vmcnt(17)
	v_cndmask_b32_e32 v162, 0, v212, vcc
	s_waitcnt vmcnt(16)
	v_cndmask_b32_e32 v180, 0, v213, vcc
	ds_write2_b32 v175, v162, v180 offset0:156 offset1:222
	s_waitcnt vmcnt(15)
	v_cndmask_b32_e32 v162, 0, v214, vcc
	s_waitcnt vmcnt(14)
	v_cndmask_b32_e32 v180, 0, v215, vcc
	ds_write2_b32 v176, v162, v180 offset0:32 offset1:98
	s_waitcnt vmcnt(13)
	v_cndmask_b32_e32 v162, 0, v216, vcc
	s_waitcnt vmcnt(12)
	v_cndmask_b32_e32 v180, 0, v217, vcc
	ds_write2_b32 v176, v162, v180 offset0:164 offset1:230
	s_waitcnt vmcnt(11)
	v_cndmask_b32_e32 v162, 0, v218, vcc
	s_waitcnt vmcnt(10)
	v_cndmask_b32_e32 v180, 0, v219, vcc
	ds_write2_b32 v177, v162, v180 offset0:40 offset1:106
	s_waitcnt vmcnt(9)
	v_cndmask_b32_e32 v162, 0, v196, vcc
	s_waitcnt vmcnt(8)
	v_cndmask_b32_e32 v180, 0, v197, vcc
	ds_write2_b32 v177, v162, v180 offset0:172 offset1:238
	s_waitcnt vmcnt(7)
	v_cndmask_b32_e32 v162, 0, v198, vcc
	s_waitcnt vmcnt(6)
	v_cndmask_b32_e32 v180, 0, v186, vcc
	ds_write2_b32 v178, v162, v180 offset0:48 offset1:114
	s_waitcnt vmcnt(5)
	v_cndmask_b32_e32 v162, 0, v187, vcc
	s_waitcnt vmcnt(4)
	v_cndmask_b32_e32 v180, 0, v188, vcc
	ds_write2_b32 v178, v162, v180 offset0:180 offset1:246
	s_waitcnt vmcnt(3)
	v_cndmask_b32_e32 v162, 0, v189, vcc
	s_waitcnt vmcnt(2)
	v_cndmask_b32_e32 v180, 0, v190, vcc
	ds_write2_b32 v179, v162, v180 offset0:56 offset1:122
	s_waitcnt vmcnt(1)
	v_cndmask_b32_e32 v162, 0, v184, vcc
	s_waitcnt vmcnt(0)
	v_cndmask_b32_e32 v180, 0, v182, vcc
	ds_write2_b32 v179, v162, v180 offset0:188 offset1:254
	s_waitcnt lgkmcnt(0)
	ds_read2_b32 v[186:187], v168 offset1:8
	ds_read2_b32 v[190:191], v168 offset0:33 offset1:41
	ds_read2_b32 v[192:193], v168 offset0:66 offset1:74
	ds_read2_b32 v[194:195], v168 offset0:99 offset1:107
	ds_read2_b32 v[196:197], v168 offset0:132 offset1:140
	s_waitcnt lgkmcnt(4)
	v_bfe_u32 v162, v186, 16, 1
	v_add3_u32 v162, v186, v162, s64
	s_waitcnt lgkmcnt(3)
	v_bfe_u32 v180, v190, 16, 1
	v_lshrrev_b32_e32 v162, 16, v162
	v_add3_u32 v180, v190, v180, s64
	ds_read2_b32 v[198:199], v168 offset0:165 offset1:173
	v_and_or_b32 v182, v180, s65, v162
	s_waitcnt lgkmcnt(3)
	v_bfe_u32 v162, v192, 16, 1
	v_add3_u32 v162, v192, v162, s64
	s_waitcnt lgkmcnt(2)
	v_bfe_u32 v180, v194, 16, 1
	ds_read2_b32 v[200:201], v168 offset0:198 offset1:206
	v_lshrrev_b32_e32 v162, 16, v162
	v_add3_u32 v180, v194, v180, s64
	ds_read2_b32 v[202:203], v168 offset0:231 offset1:239
	v_and_or_b32 v183, v180, s65, v162
	s_waitcnt lgkmcnt(3)
	v_bfe_u32 v162, v196, 16, 1
	v_add3_u32 v162, v196, v162, s64
	s_waitcnt lgkmcnt(2)
	v_bfe_u32 v180, v198, 16, 1
	v_lshrrev_b32_e32 v162, 16, v162
	v_add3_u32 v180, v198, v180, s64
	v_and_or_b32 v184, v180, s65, v162
	s_waitcnt lgkmcnt(1)
	v_bfe_u32 v162, v200, 16, 1
	v_add3_u32 v162, v200, v162, s64
	s_waitcnt lgkmcnt(0)
	v_bfe_u32 v180, v202, 16, 1
	v_lshrrev_b32_e32 v162, 16, v162
	v_add3_u32 v180, v202, v180, s64
	v_lshl_add_u64 v[188:189], s[36:37], 0, v[164:165]
	v_and_or_b32 v185, v180, s65, v162
	v_add_lshl_u32 v162, s66, v181, 11
	v_lshl_add_u64 v[204:205], v[188:189], 0, v[162:163]
	v_bfe_u32 v162, v187, 16, 1
	v_add3_u32 v162, v187, v162, s64
	v_bfe_u32 v180, v191, 16, 1
	v_lshrrev_b32_e32 v162, 16, v162
	v_add3_u32 v180, v191, v180, s64
	global_store_dwordx4 v[204:205], v[182:185], off sc1
	ds_read2_b32 v[186:187], v168 offset0:16 offset1:24
	v_readlane_b32 s36, v254, 11
	v_and_or_b32 v182, v180, s65, v162
	v_bfe_u32 v162, v193, 16, 1
	v_add3_u32 v162, v193, v162, s64
	v_bfe_u32 v180, v195, 16, 1
	v_lshrrev_b32_e32 v162, 16, v162
	v_add3_u32 v180, v195, v180, s64
	v_and_or_b32 v183, v180, s65, v162
	v_bfe_u32 v162, v197, 16, 1
	v_add3_u32 v162, v197, v162, s64
	v_bfe_u32 v180, v199, 16, 1
	v_lshrrev_b32_e32 v162, 16, v162
	v_add3_u32 v180, v199, v180, s64
	v_and_or_b32 v184, v180, s65, v162
	v_bfe_u32 v162, v201, 16, 1
	v_add3_u32 v162, v201, v162, s64
	v_bfe_u32 v180, v203, 16, 1
	v_lshrrev_b32_e32 v162, 16, v162
	v_add3_u32 v180, v203, v180, s64
	v_and_or_b32 v185, v180, s65, v162
	v_add_lshl_u32 v162, s66, v169, 11
	v_lshl_add_u64 v[190:191], v[188:189], 0, v[162:163]
	global_store_dwordx4 v[190:191], v[182:185], off sc1
	ds_read2_b32 v[190:191], v168 offset0:49 offset1:57
	ds_read2_b32 v[192:193], v168 offset0:82 offset1:90
	ds_read2_b32 v[194:195], v168 offset0:115 offset1:123
	s_waitcnt lgkmcnt(3)
	v_bfe_u32 v162, v186, 16, 1
	v_add3_u32 v162, v186, v162, s64
	s_waitcnt lgkmcnt(2)
	v_bfe_u32 v180, v190, 16, 1
	ds_read2_b32 v[196:197], v168 offset0:148 offset1:156
	v_lshrrev_b32_e32 v162, 16, v162
	v_add3_u32 v180, v190, v180, s64
	ds_read2_b32 v[198:199], v168 offset0:181 offset1:189
	v_and_or_b32 v182, v180, s65, v162
	s_waitcnt lgkmcnt(3)
	v_bfe_u32 v162, v192, 16, 1
	v_add3_u32 v162, v192, v162, s64
	s_waitcnt lgkmcnt(2)
	v_bfe_u32 v180, v194, 16, 1
	ds_read2_b32 v[200:201], v168 offset0:214 offset1:222
	v_lshrrev_b32_e32 v162, 16, v162
	v_add3_u32 v180, v194, v180, s64
	ds_read2_b32 v[202:203], v168 offset0:247 offset1:255
	v_and_or_b32 v183, v180, s65, v162
	s_waitcnt lgkmcnt(3)
	v_bfe_u32 v162, v196, 16, 1
	v_add3_u32 v162, v196, v162, s64
	s_waitcnt lgkmcnt(2)
	v_bfe_u32 v180, v198, 16, 1
	v_lshrrev_b32_e32 v162, 16, v162
	v_add3_u32 v180, v198, v180, s64
	v_and_or_b32 v184, v180, s65, v162
	s_waitcnt lgkmcnt(1)
	v_bfe_u32 v162, v200, 16, 1
	v_add3_u32 v162, v200, v162, s64
	s_waitcnt lgkmcnt(0)
	v_bfe_u32 v180, v202, 16, 1
	v_lshrrev_b32_e32 v162, 16, v162
	v_add3_u32 v180, v202, v180, s64
	v_and_or_b32 v185, v180, s65, v162
	v_add_lshl_u32 v162, s66, v170, 11
	v_lshl_add_u64 v[204:205], v[188:189], 0, v[162:163]
	v_bfe_u32 v162, v187, 16, 1
	v_add3_u32 v162, v187, v162, s64
	v_bfe_u32 v180, v191, 16, 1
	v_lshrrev_b32_e32 v162, 16, v162
	v_add3_u32 v180, v191, v180, s64
	global_store_dwordx4 v[204:205], v[182:185], off sc1
	s_add_i32 s33, s33, s36
	s_cmpk_gt_i32 s33, 0xc7f
	v_and_or_b32 v182, v180, s65, v162
	v_bfe_u32 v162, v193, 16, 1
	v_add3_u32 v162, v193, v162, s64
	v_bfe_u32 v180, v195, 16, 1
	v_lshrrev_b32_e32 v162, 16, v162
	v_add3_u32 v180, v195, v180, s64
	v_and_or_b32 v183, v180, s65, v162
	v_bfe_u32 v162, v197, 16, 1
	v_add3_u32 v162, v197, v162, s64
	v_bfe_u32 v180, v199, 16, 1
	v_lshrrev_b32_e32 v162, 16, v162
	v_add3_u32 v180, v199, v180, s64
	v_and_or_b32 v184, v180, s65, v162
	v_bfe_u32 v162, v201, 16, 1
	v_add3_u32 v162, v201, v162, s64
	v_bfe_u32 v180, v203, 16, 1
	v_lshrrev_b32_e32 v162, 16, v162
	v_add3_u32 v180, v203, v180, s64
	v_and_or_b32 v185, v180, s65, v162
	v_add_lshl_u32 v162, s66, v171, 11
	v_lshl_add_u64 v[186:187], v[188:189], 0, v[162:163]
	global_store_dwordx4 v[186:187], v[182:185], off sc1
	s_waitcnt lgkmcnt(0)
	v_readlane_b32 s37, v254, 12
	s_cbranch_scc1 .LBB0_130

.LBB0_165:
	v_lshl_add_u64 v[120:121], v[128:129], 0, s[50:51]
	v_lshl_add_u64 v[122:123], v[134:135], 0, s[82:83]
	v_lshl_add_u64 v[124:125], v[132:133], 0, s[82:83]
	v_cmp_gt_u64_e32 vcc, s[42:43], v[120:121]
	v_lshl_add_u64 v[226:227], v[128:129], 0, s[46:47]
	v_cmp_gt_u64_e64 s[26:27], s[34:35], v[226:227]
	v_cndmask_b32_e32 v125, v125, v123, vcc
	v_cndmask_b32_e32 v124, v124, v122, vcc
	global_load_dwordx4 v[120:123], v[124:125], off offset:16 nt
	s_nop 0
	global_load_dwordx4 v[124:127], v[124:125], off nt
	s_and_saveexec_b64 s[0:1], s[26:27]
	s_cbranch_execz .LBB0_167
	v_lshl_add_u64 v[0:1], v[224:225], 0, s[82:83]
	v_lshl_add_u64 v[2:3], v[222:223], 0, s[82:83]
	v_cmp_gt_u64_e32 vcc, s[42:43], v[226:227]
	s_nop 1
	v_cndmask_b32_e32 v5, v3, v1, vcc
	v_cndmask_b32_e32 v4, v2, v0, vcc
	global_load_dwordx4 v[0:3], v[4:5], off offset:16 nt
	s_nop 0
	global_load_dwordx4 v[4:7], v[4:5], off nt
.LBB0_167:
	s_or_b64 exec, exec, s[0:1]
	v_lshl_add_u64 v[226:227], v[128:129], 0, s[52:53]
	v_cmp_gt_u64_e64 s[24:25], s[34:35], v[226:227]
	s_and_saveexec_b64 s[0:1], s[24:25]
	s_cbranch_execz .LBB0_169
	v_lshl_add_u64 v[8:9], v[138:139], 0, s[82:83]
	v_lshl_add_u64 v[10:11], v[136:137], 0, s[82:83]
	v_cmp_gt_u64_e32 vcc, s[42:43], v[226:227]
	s_nop 1
	v_cndmask_b32_e32 v13, v11, v9, vcc
	v_cndmask_b32_e32 v12, v10, v8, vcc
	global_load_dwordx4 v[8:11], v[12:13], off offset:16 nt
	s_nop 0
	global_load_dwordx4 v[12:15], v[12:13], off nt
.LBB0_169:
	s_or_b64 exec, exec, s[0:1]
	v_lshl_add_u64 v[226:227], v[128:129], 0, s[54:55]
	v_cmp_gt_u64_e64 s[22:23], s[34:35], v[226:227]
	s_and_saveexec_b64 s[0:1], s[22:23]
	s_cbranch_execz .LBB0_171
	v_lshl_add_u64 v[16:17], v[144:145], 0, s[82:83]
	v_lshl_add_u64 v[18:19], v[142:143], 0, s[82:83]
	v_cmp_gt_u64_e32 vcc, s[42:43], v[226:227]
	s_nop 1
	v_cndmask_b32_e32 v21, v19, v17, vcc
	v_cndmask_b32_e32 v20, v18, v16, vcc
	global_load_dwordx4 v[16:19], v[20:21], off offset:16 nt
	s_nop 0
	global_load_dwordx4 v[20:23], v[20:21], off nt
.LBB0_171:
	s_or_b64 exec, exec, s[0:1]
	v_lshl_add_u64 v[226:227], v[128:129], 0, s[58:59]
	v_cmp_gt_u64_e64 s[20:21], s[34:35], v[226:227]
	s_and_saveexec_b64 s[0:1], s[20:21]
	s_cbranch_execz .LBB0_173
	v_lshl_add_u64 v[24:25], v[150:151], 0, s[82:83]
	v_lshl_add_u64 v[26:27], v[148:149], 0, s[82:83]
	v_cmp_gt_u64_e32 vcc, s[42:43], v[226:227]
	s_nop 1
	v_cndmask_b32_e32 v29, v27, v25, vcc
	v_cndmask_b32_e32 v28, v26, v24, vcc
	global_load_dwordx4 v[24:27], v[28:29], off offset:16 nt
	s_nop 0
	global_load_dwordx4 v[28:31], v[28:29], off nt
.LBB0_173:
	s_or_b64 exec, exec, s[0:1]
	v_lshl_add_u64 v[226:227], v[128:129], 0, s[60:61]
	v_cmp_gt_u64_e64 s[18:19], s[34:35], v[226:227]
	s_and_saveexec_b64 s[0:1], s[18:19]
	s_cbranch_execz .LBB0_175
	v_lshl_add_u64 v[32:33], v[156:157], 0, s[82:83]
	v_lshl_add_u64 v[34:35], v[154:155], 0, s[82:83]
	v_cmp_gt_u64_e32 vcc, s[42:43], v[226:227]
	s_nop 1
	v_cndmask_b32_e32 v37, v35, v33, vcc
	v_cndmask_b32_e32 v36, v34, v32, vcc
	global_load_dwordx4 v[32:35], v[36:37], off offset:16 nt
	s_nop 0
	global_load_dwordx4 v[36:39], v[36:37], off nt
.LBB0_175:
	s_or_b64 exec, exec, s[0:1]
	v_lshl_add_u64 v[226:227], v[128:129], 0, s[62:63]
	v_cmp_gt_u64_e64 s[16:17], s[34:35], v[226:227]
	s_and_saveexec_b64 s[0:1], s[16:17]
	s_cbranch_execz .LBB0_177
	v_lshl_add_u64 v[40:41], v[162:163], 0, s[82:83]
	v_lshl_add_u64 v[42:43], v[160:161], 0, s[82:83]
	v_cmp_gt_u64_e32 vcc, s[42:43], v[226:227]
	s_nop 1
	v_cndmask_b32_e32 v45, v43, v41, vcc
	v_cndmask_b32_e32 v44, v42, v40, vcc
	global_load_dwordx4 v[40:43], v[44:45], off offset:16 nt
	s_nop 0
	global_load_dwordx4 v[44:47], v[44:45], off nt
.LBB0_177:
	s_or_b64 exec, exec, s[0:1]
	v_lshl_add_u64 v[226:227], v[128:129], 0, s[64:65]
	v_cmp_gt_u64_e64 s[14:15], s[34:35], v[226:227]
	s_and_saveexec_b64 s[0:1], s[14:15]
	s_cbranch_execz .LBB0_179
	v_lshl_add_u64 v[48:49], v[168:169], 0, s[82:83]
	v_lshl_add_u64 v[50:51], v[166:167], 0, s[82:83]
	v_cmp_gt_u64_e32 vcc, s[42:43], v[226:227]
	s_nop 1
	v_cndmask_b32_e32 v53, v51, v49, vcc
	v_cndmask_b32_e32 v52, v50, v48, vcc
	global_load_dwordx4 v[48:51], v[52:53], off offset:16 nt
	s_nop 0
	global_load_dwordx4 v[52:55], v[52:53], off nt
.LBB0_179:
	s_or_b64 exec, exec, s[0:1]
	v_lshl_add_u64 v[226:227], v[128:129], 0, s[66:67]
	v_cmp_gt_u64_e64 s[12:13], s[34:35], v[226:227]
	s_and_saveexec_b64 s[0:1], s[12:13]
	s_cbranch_execz .LBB0_181
	v_lshl_add_u64 v[56:57], v[174:175], 0, s[82:83]
	v_lshl_add_u64 v[58:59], v[172:173], 0, s[82:83]
	v_cmp_gt_u64_e32 vcc, s[42:43], v[226:227]
	s_nop 1
	v_cndmask_b32_e32 v61, v59, v57, vcc
	v_cndmask_b32_e32 v60, v58, v56, vcc
	global_load_dwordx4 v[56:59], v[60:61], off offset:16 nt
	s_nop 0
	global_load_dwordx4 v[60:63], v[60:61], off nt
.LBB0_181:
	s_or_b64 exec, exec, s[0:1]
	v_lshl_add_u64 v[226:227], v[128:129], 0, s[68:69]
	v_cmp_gt_u64_e64 s[10:11], s[34:35], v[226:227]
	s_and_saveexec_b64 s[0:1], s[10:11]
	s_cbranch_execz .LBB0_183
	v_lshl_add_u64 v[64:65], v[180:181], 0, s[82:83]
	v_lshl_add_u64 v[66:67], v[178:179], 0, s[82:83]
	v_cmp_gt_u64_e32 vcc, s[42:43], v[226:227]
	s_nop 1
	v_cndmask_b32_e32 v69, v67, v65, vcc
	v_cndmask_b32_e32 v68, v66, v64, vcc
	global_load_dwordx4 v[64:67], v[68:69], off offset:16 nt
	s_nop 0
	global_load_dwordx4 v[68:71], v[68:69], off nt
.LBB0_183:
	s_or_b64 exec, exec, s[0:1]
	v_lshl_add_u64 v[226:227], v[128:129], 0, s[70:71]
	v_cmp_gt_u64_e64 s[8:9], s[34:35], v[226:227]
	s_and_saveexec_b64 s[0:1], s[8:9]
	s_cbranch_execz .LBB0_185
	v_lshl_add_u64 v[72:73], v[186:187], 0, s[82:83]
	v_lshl_add_u64 v[74:75], v[184:185], 0, s[82:83]
	v_cmp_gt_u64_e32 vcc, s[42:43], v[226:227]
	s_nop 1
	v_cndmask_b32_e32 v77, v75, v73, vcc
	v_cndmask_b32_e32 v76, v74, v72, vcc
	global_load_dwordx4 v[72:75], v[76:77], off offset:16 nt
	s_nop 0
	global_load_dwordx4 v[76:79], v[76:77], off nt
.LBB0_185:
	s_or_b64 exec, exec, s[0:1]
	v_lshl_add_u64 v[226:227], v[128:129], 0, s[72:73]
	v_cmp_gt_u64_e64 s[6:7], s[34:35], v[226:227]
	s_and_saveexec_b64 s[0:1], s[6:7]
	s_cbranch_execz .LBB0_187
	v_lshl_add_u64 v[80:81], v[192:193], 0, s[82:83]
	v_lshl_add_u64 v[82:83], v[190:191], 0, s[82:83]
	v_cmp_gt_u64_e32 vcc, s[42:43], v[226:227]
	s_nop 1
	v_cndmask_b32_e32 v85, v83, v81, vcc
	v_cndmask_b32_e32 v84, v82, v80, vcc
	global_load_dwordx4 v[80:83], v[84:85], off offset:16 nt
	s_nop 0
	global_load_dwordx4 v[84:87], v[84:85], off nt
.LBB0_187:
	s_or_b64 exec, exec, s[0:1]
	v_lshl_add_u64 v[226:227], v[128:129], 0, s[74:75]
	v_cmp_gt_u64_e64 s[4:5], s[34:35], v[226:227]
	s_and_saveexec_b64 s[0:1], s[4:5]
	s_cbranch_execz .LBB0_189
	v_lshl_add_u64 v[88:89], v[198:199], 0, s[82:83]
	v_lshl_add_u64 v[90:91], v[196:197], 0, s[82:83]
	v_cmp_gt_u64_e32 vcc, s[42:43], v[226:227]
	s_nop 1
	v_cndmask_b32_e32 v93, v91, v89, vcc
	v_cndmask_b32_e32 v92, v90, v88, vcc
	global_load_dwordx4 v[88:91], v[92:93], off offset:16 nt
	s_nop 0
	global_load_dwordx4 v[92:95], v[92:93], off nt
.LBB0_189:
	s_or_b64 exec, exec, s[0:1]
	v_lshl_add_u64 v[226:227], v[128:129], 0, s[76:77]
	v_cmp_gt_u64_e64 s[2:3], s[34:35], v[226:227]
	s_and_saveexec_b64 s[0:1], s[2:3]
	s_cbranch_execz .LBB0_191
	v_lshl_add_u64 v[96:97], v[204:205], 0, s[82:83]
	v_lshl_add_u64 v[98:99], v[202:203], 0, s[82:83]
	v_cmp_gt_u64_e32 vcc, s[42:43], v[226:227]
	s_nop 1
	v_cndmask_b32_e32 v101, v99, v97, vcc
	v_cndmask_b32_e32 v100, v98, v96, vcc
	global_load_dwordx4 v[96:99], v[100:101], off offset:16 nt
	s_nop 0
	global_load_dwordx4 v[100:103], v[100:101], off nt
.LBB0_191:
	s_or_b64 exec, exec, s[0:1]
	v_lshl_add_u64 v[226:227], v[128:129], 0, s[78:79]
	v_cmp_gt_u64_e64 s[0:1], s[34:35], v[226:227]
	s_and_saveexec_b64 s[28:29], s[0:1]
	s_cbranch_execz .LBB0_193
	v_lshl_add_u64 v[104:105], v[210:211], 0, s[82:83]
	v_lshl_add_u64 v[106:107], v[208:209], 0, s[82:83]
	v_cmp_gt_u64_e32 vcc, s[42:43], v[226:227]
	s_nop 1
	v_cndmask_b32_e32 v109, v107, v105, vcc
	v_cndmask_b32_e32 v108, v106, v104, vcc
	global_load_dwordx4 v[104:107], v[108:109], off offset:16 nt
	s_nop 0
	global_load_dwordx4 v[108:111], v[108:109], off nt
.LBB0_193:
	s_or_b64 exec, exec, s[28:29]
	v_lshl_add_u64 v[226:227], v[128:129], 0, s[80:81]
	v_cmp_gt_u64_e32 vcc, s[34:35], v[226:227]
	s_and_saveexec_b64 s[84:85], vcc
	s_cbranch_execz .LBB0_195
	v_lshl_add_u64 v[112:113], v[216:217], 0, s[82:83]
	v_lshl_add_u64 v[114:115], v[214:215], 0, s[82:83]
	v_cmp_gt_u64_e64 s[28:29], s[42:43], v[226:227]
	s_nop 1
	v_cndmask_b32_e64 v117, v115, v113, s[28:29]
	v_cndmask_b32_e64 v116, v114, v112, s[28:29]
	global_load_dwordx4 v[112:115], v[116:117], off offset:16 nt
	s_nop 0
	global_load_dwordx4 v[116:119], v[116:117], off nt
